# lever 4 on the dilated-attention phase: static s_setprio 1 for waves 4-7, reset at phase end
# baseline (speedup 1.0000x reference)
; __device__ __forceinline__ void dil_unit(const bf16_t* QKV, float* scr, bf16_t* O, int b, int h, int blk, char* shm) {
;     ...
;     for (int br = 0; br < 3; ++br) {
;         const int lg = 2 * br, d = 1 << lg;
;         const float sl = slope2 * (float)d;
; #pragma unroll 1
;         for (int rep = 0; rep < 2; ++rep) {
; __global__ void __launch_bounds__(NTHR, 2) mk_fwd(Args a) {
;     ...
;                     const int xg = bid & 7, li = bid >> 3, h = li >> 2, blk = li & 3;
;                     for (int r = 0; r < 2; ++r) att::dil_unit(AQKV, (float*)(ws + WS_DIL + (size_t)bid * DIL_SCR_BYTES), O0, 2 * xg + r, h, blk, (char*)lds);
.LBB0_1132:
	s_setprio 0
	s_add_i32 s0, s7, -1
	s_cmp_lt_i32 s7, 2
	s_mov_b32 s7, s0
	s_cbranch_scc1 .LBB0_1263

; __device__ __forceinline__ void dil_unit(const bf16_t* QKV, float* scr, bf16_t* O, int b, int h, int blk, char* shm) {
;     ...
;         __threadfence_block();
;         __syncthreads();
.LBB0_1241:
	s_mov_b32 s3, 0
	s_mov_b64 s[0:1], -1
	s_waitcnt lgkmcnt(0)
	s_barrier
	v_readfirstlane_b32 s8, v238
	s_nop 3
	s_cmp_ge_u32 s8, 0x100
	s_cbranch_scc0 .Ldil_prio_lo
	s_setprio 1
.Ldil_prio_lo:
	s_branch .LBB0_1243
.LBB0_1242:
	s_mov_b32 s3, 1
	s_mov_b64 s[0:1], 0
	s_and_b64 vcc, exec, s[26:27]
	s_cbranch_vccnz .LBB0_1132
